# softplus in the GDN/SSD chunk loops: log1p(e) via log(1+e)*e/((1+e)-1) in f32 instead of the 115-instruction double-float expansion
# speedup vs baseline: 1.0326x; 1.0080x over previous
; __device__ __forceinline__ float softplusf_(float x) { return x > 20.f ? x : log1pf(expf(x)); }
; template <int MIX>
; __device__ __forceinline__ void ch_process(const Raw<MIX>& R, const MixPar& par, LAS unsigned char* B, int chunk) {
;     ...
;         const float dt = softplusf_(R.dt + par.f[0]);
.LBB0_179:
	s_waitcnt vmcnt(5)
	v_cvt_f32_f16_e32 v75, v75
	s_nop 0
	v_add_f32_e32 v12, v65, v75
	v_mov_b32_e32 v13, v202
	v_cmp_nlt_f32_e32 vcc, s23, v12
	s_and_saveexec_b64 s[4:5], vcc
	s_cbranch_execz .LBB0_181
	v_mul_f32_e32 v14, 0x3fb8aa3b, v12
	v_rndne_f32_e32 v15, v14
	v_sub_f32_e32 v16, v14, v15
	v_fma_f32 v14, v12, s19, -v14
	v_fmac_f32_e32 v14, 0x32a5705f, v12
	v_add_f32_e32 v14, v16, v14
	v_cvt_i32_f32_e32 v15, v15
	v_exp_f32_e32 v14, v14
	v_cmp_ngt_f32_e32 vcc, s96, v12
	v_ldexp_f32 v14, v14, v15
	s_nop 0
	v_cndmask_b32_e32 v14, 0, v14, vcc
	v_cmp_nlt_f32_e32 vcc, s97, v12
	s_nop 1
	v_cndmask_b32_e32 v12, v216, v14, vcc
	v_add_f32_e32 v16, 1.0, v12
	v_add_f32_e32 v14, -1.0, v16
	v_log_f32_e32 v15, v16
	v_rcp_f32_e32 v16, v14
	v_cmp_eq_f32_e32 vcc, 0, v14
	v_mul_f32_e32 v15, 0x3f317218, v15
	v_mul_f32_e32 v16, v12, v16
	v_mul_f32_e32 v15, v15, v16
	v_cndmask_b32_e32 v12, v15, v12, vcc

; #define LAS __attribute__((address_space(3)))
; __device__ __forceinline__ float sigmoidf_(float x) { return 1.0f / (1.0f + __expf(-x)); }
; __device__ __forceinline__ float red8(float x) { x = red4(x); x += dppf<0x141>(x); return x; }
; __device__ __forceinline__ void u4f(const u32x4& u, float (&f)[8]) { h2f(u.x, f[0], f[1]); h2f(u.y, f[2], f[3]); h2f(u.z, f[4], f[5]); h2f(u.w, f[6], f[7]); }
; __device__ __forceinline__ void u2f(const u32x2& u, float (&f)[4]) { h2f(u.x, f[0], f[1]); h2f(u.y, f[2], f[3]); }
; __device__ __forceinline__ float softplusf_(float x) { return x > 20.f ? x : log1pf(expf(x)); }
; template <int MIX, bool SAMPLE>
; __device__ __forceinline__ void rec_process(const Raw<MIX>& R, const MixPar& par, int l, LAS float* L, int chunk, int sg, int head) {
;     ...
;     } else if constexpr (MIX == 1) {
;         float q[8], k[8], v[4]; u4f(R.q, q); u4f(R.k, k); u2f(R.v, v);
;         float sq = 0.f, sk = 0.f;
; #pragma unroll
;         for (int i = 0; i < 8; ++i) { sq += q[i] * q[i]; sk += k[i] * k[i]; }
;         sq = red8(sq); sk = red8(sk);
;         const float rq = rsqrtf(sq + EPS) * 0.125f, rk = rsqrtf(sk + EPS);
;         float kq = 0.f;
; #pragma unroll
;         for (int i = 0; i < 8; ++i) { q[i] *= rq; k[i] *= rk; kq += q[i] * k[i]; }
;         kq = red8(kq);
;         *(LAS f32x4*)(L + C::OFF_Q + s * 64 + cgi * 8) = (f32x4){q[0], q[1], q[2], q[3]}; *(LAS f32x4*)(L + C::OFF_Q + s * 64 + cgi * 8 + 4) = (f32x4){q[4], q[5], q[6], q[7]};
;         *(LAS f32x4*)(L + C::OFF_K + s * 64 + cgi * 8) = (f32x4){k[0], k[1], k[2], k[3]}; *(LAS f32x4*)(L + C::OFF_K + s * 64 + cgi * 8 + 4) = (f32x4){k[4], k[5], k[6], k[7]};
;         *(LAS f32x4*)(L + C::OFF_V + s * 32 + cgi * 4) = (f32x4){v[0], v[1], v[2], v[3]};
;         if (cgi == 0) { const float a = expf(-par.f[0] * softplusf_(R.ga + par.f[1]));
;             *(LAS f32x4*)(L + C::OFF_SC + s * 4) = (f32x4){a, sigmoidf_(R.gb), kq, 0.f}; }
.LBB0_413:
	s_or_b64 exec, exec, s[6:7]
	s_add_i32 s2, s12, 1
	s_cmp_lg_u32 s12, 31
	s_cbranch_scc0 .LBB0_420
	s_waitcnt vmcnt(2)
	v_cvt_f32_f16_e32 v23, v23
	v_cvt_f32_f16_e32 v24, v24
	v_cvt_f32_f16_sdwa v31, v0 dst_sel:DWORD dst_unused:UNUSED_PAD src0_sel:WORD_1
	v_cvt_f32_f16_e32 v30, v0
	s_waitcnt vmcnt(1)
	v_cvt_f32_f16_sdwa v47, v4 dst_sel:DWORD dst_unused:UNUSED_PAD src0_sel:WORD_1
	v_cvt_f32_f16_e32 v46, v4
	v_cvt_f32_f16_sdwa v41, v1 dst_sel:DWORD dst_unused:UNUSED_PAD src0_sel:WORD_1
	v_cvt_f32_f16_e32 v40, v1
	v_cvt_f32_f16_sdwa v49, v5 dst_sel:DWORD dst_unused:UNUSED_PAD src0_sel:WORD_1
	v_cvt_f32_f16_e32 v48, v5
	v_cvt_f32_f16_sdwa v15, v2 dst_sel:DWORD dst_unused:UNUSED_PAD src0_sel:WORD_1
	v_cvt_f32_f16_e32 v14, v2
	v_cvt_f32_f16_sdwa v43, v6 dst_sel:DWORD dst_unused:UNUSED_PAD src0_sel:WORD_1
	v_cvt_f32_f16_e32 v42, v6
	v_pk_mul_f32 v[38:39], v[30:31], v[30:31]
	v_pk_mul_f32 v[54:55], v[46:47], v[46:47]
	v_cvt_f32_f16_sdwa v37, v3 dst_sel:DWORD dst_unused:UNUSED_PAD src0_sel:WORD_1
	v_cvt_f32_f16_e32 v36, v3
	v_cvt_f32_f16_sdwa v45, v7 dst_sel:DWORD dst_unused:UNUSED_PAD src0_sel:WORD_1
	v_cvt_f32_f16_e32 v44, v7
	v_pk_mul_f32 v[50:51], v[40:41], v[40:41]
	v_pk_mul_f32 v[56:57], v[48:49], v[48:49]
	v_mov_b32_e32 v58, v54
	v_mov_b32_e32 v59, v38
	v_mov_b32_e32 v38, v55
	v_pk_add_f32 v[38:39], v[58:59], v[38:39]
	v_mov_b32_e32 v54, v56
	v_mov_b32_e32 v55, v50
	v_pk_mul_f32 v[28:29], v[14:15], v[14:15]
	v_pk_mul_f32 v[32:33], v[42:43], v[42:43]
	v_pk_add_f32 v[38:39], v[54:55], v[38:39]
	v_mov_b32_e32 v50, v57
	v_pk_add_f32 v[38:39], v[50:51], v[38:39]
	v_mov_b32_e32 v50, v32
	v_mov_b32_e32 v51, v28
	v_pk_mul_f32 v[34:35], v[36:37], v[36:37]
	v_pk_mul_f32 v[52:53], v[44:45], v[44:45]
	v_pk_add_f32 v[38:39], v[50:51], v[38:39]
	v_mov_b32_e32 v28, v33
	v_pk_add_f32 v[28:29], v[28:29], v[38:39]
	v_mov_b32_e32 v32, v52
	v_mov_b32_e32 v33, v34
	v_pk_add_f32 v[28:29], v[32:33], v[28:29]
	v_mov_b32_e32 v34, v53
	v_pk_add_f32 v[28:29], v[34:35], v[28:29]
	s_bitcmp1_b32 s2, 0
	s_cselect_b32 s3, 0xe400, 0
	v_mov_b32_dpp v33, v29 quad_perm:[1,0,3,2] row_mask:0xf bank_mask:0xf bound_ctrl:1
	v_mov_b32_dpp v32, v28 quad_perm:[1,0,3,2] row_mask:0xf bank_mask:0xf bound_ctrl:1
	v_pk_add_f32 v[28:29], v[28:29], v[32:33]
	s_add_i32 s3, s3, 0
	s_nop 0
	v_mov_b32_dpp v33, v29 quad_perm:[2,3,0,1] row_mask:0xf bank_mask:0xf bound_ctrl:1
	v_mov_b32_dpp v32, v28 quad_perm:[2,3,0,1] row_mask:0xf bank_mask:0xf bound_ctrl:1
	v_pk_add_f32 v[28:29], v[28:29], v[32:33]
	s_nop 1
	v_mov_b32_dpp v33, v29 row_half_mirror row_mask:0xf bank_mask:0xf bound_ctrl:1
	v_mov_b32_dpp v32, v28 row_half_mirror row_mask:0xf bank_mask:0xf bound_ctrl:1
	v_pk_add_f32 v[28:29], v[28:29], v[32:33]
	s_nop 0
	v_pk_add_f32 v[32:33], v[28:29], s[66:67] op_sel_hi:[1,0]
	v_mov_b32_e32 v29, v202
	v_mul_f32_e32 v16, 0x4b800000, v33
	v_cmp_gt_f32_e32 vcc, s16, v33
	s_nop 0
	v_ashrrev_i32_e32 v28, 3, v29
	v_cndmask_b32_e32 v16, v33, v16, vcc
	v_rsq_f32_e32 v16, v16
	s_nop 0
	v_mul_f32_e32 v33, 0x45800000, v16
	v_cndmask_b32_e32 v16, v16, v33, vcc
	v_mul_f32_e32 v33, 0x4b800000, v32
	v_cmp_gt_f32_e32 vcc, s16, v32
	v_mul_f32_e32 v16, 0x3e000000, v16
	v_pk_mul_f32 v[34:35], v[16:17], v[14:15] op_sel_hi:[0,1]
	v_cndmask_b32_e32 v32, v32, v33, vcc
	v_rsq_f32_e32 v38, v32
	v_pk_mul_f32 v[30:31], v[16:17], v[30:31] op_sel_hi:[0,1]
	v_pk_mul_f32 v[32:33], v[16:17], v[40:41] op_sel_hi:[0,1]
	v_pk_mul_f32 v[36:37], v[16:17], v[36:37] op_sel_hi:[0,1]
	v_mul_f32_e32 v14, 0x45800000, v38
	v_cndmask_b32_e32 v14, v38, v14, vcc
	v_pk_mul_f32 v[38:39], v[14:15], v[46:47] op_sel_hi:[0,1]
	v_pk_mul_f32 v[40:41], v[30:31], v[38:39]
	s_nop 0
	v_add_f32_e32 v15, 0, v40
	v_add_f32_e32 v15, v41, v15
	v_pk_mul_f32 v[40:41], v[14:15], v[48:49] op_sel_hi:[0,1]
	v_pk_mul_f32 v[46:47], v[32:33], v[40:41]
	v_cvt_f32_f16_sdwa v49, v9 dst_sel:DWORD dst_unused:UNUSED_PAD src0_sel:WORD_1
	v_add_f32_e32 v15, v46, v15
	v_add_f32_e32 v15, v47, v15
	v_pk_mul_f32 v[42:43], v[14:15], v[42:43] op_sel_hi:[0,1]
	v_pk_mul_f32 v[46:47], v[34:35], v[42:43]
	v_cvt_f32_f16_e32 v48, v9
	v_add_f32_e32 v15, v46, v15
	v_pk_mul_f32 v[44:45], v[14:15], v[44:45] op_sel_hi:[0,1]
	v_add_f32_e32 v16, v47, v15
	v_pk_mul_f32 v[14:15], v[36:37], v[44:45]
	v_cvt_f32_f16_sdwa v47, v8 dst_sel:DWORD dst_unused:UNUSED_PAD src0_sel:WORD_1
	v_add_f32_e32 v14, v14, v16
	v_and_b32_e32 v16, 7, v29
	v_add_f32_e32 v14, v15, v14
	v_cvt_f32_f16_e32 v46, v8
	v_lshlrev_b32_e32 v29, 8, v28
	v_lshlrev_b32_e32 v50, 5, v16
	v_add_f32_dpp v14, v14, v14 quad_perm:[1,0,3,2] row_mask:0xf bank_mask:0xf bound_ctrl:1
	v_add3_u32 v29, s3, v29, v50
	ds_write_b128 v29, v[30:33]
	ds_write_b128 v29, v[34:37] offset:16
	ds_write_b128 v29, v[38:41] offset:16384
	ds_write_b128 v29, v[42:45] offset:16400
	v_add_f32_dpp v14, v14, v14 quad_perm:[2,3,0,1] row_mask:0xf bank_mask:0xf bound_ctrl:1
	v_lshlrev_b32_e32 v29, 7, v28
	v_lshlrev_b32_e32 v30, 4, v16
	v_mov_b32_dpp v15, v14 row_half_mirror row_mask:0xf bank_mask:0xf bound_ctrl:1
	v_add3_u32 v29, s3, v29, v30
	v_cmp_eq_u32_e32 vcc, 0, v16
	ds_write_b128 v29, v[46:49] offset:32768
	s_and_saveexec_b64 s[6:7], vcc
	s_cbranch_execz .LBB0_418
	v_add_f32_e32 v16, v18, v23
	v_cmp_nlt_f32_e32 vcc, s23, v16
	s_and_saveexec_b64 s[8:9], vcc
	s_cbranch_execz .LBB0_417
	v_mul_f32_e32 v29, 0x3fb8aa3b, v16
	v_rndne_f32_e32 v30, v29
	v_sub_f32_e32 v31, v29, v30
	v_fma_f32 v29, v16, s19, -v29
	v_fmac_f32_e32 v29, 0x32a5705f, v16
	v_add_f32_e32 v29, v31, v29
	v_cvt_i32_f32_e32 v30, v30
	v_exp_f32_e32 v29, v29
	v_cmp_ngt_f32_e32 vcc, s96, v16
	v_ldexp_f32 v29, v29, v30
	s_nop 0
	v_cndmask_b32_e32 v29, 0, v29, vcc
	v_cmp_nlt_f32_e32 vcc, s97, v16
	s_nop 1
	v_cndmask_b32_e32 v16, v216, v29, vcc
	v_add_f32_e32 v29, 1.0, v16
	v_add_f32_e32 v30, -1.0, v29
	v_log_f32_e32 v31, v29
	v_rcp_f32_e32 v29, v30
	v_cmp_eq_f32_e32 vcc, 0, v30
	v_mul_f32_e32 v31, 0x3f317218, v31
	v_mul_f32_e32 v29, v16, v29
	v_mul_f32_e32 v31, v31, v29
	v_cndmask_b32_e32 v16, v31, v16, vcc
